# resid tail half-tiles (NT=2 loop) also on the LDS-DMA double-buffered K-loop
# baseline (speedup 1.0000x reference)
; template <int NT>
; __device__ __forceinline__ void gemm_tile(f32x4 (&acc)[4][NT], const bf16_t* A, int lda, const bf16_t* B, int ldb, int K, bf16_t* sm) {
;     ...
;     const int tid = tid_, lane = tid & 63, wid = tid >> 6, wr = wid >> 1, wc = wid & 1;
;     const int fr = lane & 15, fq = lane >> 4;
;     const int lrow = tid >> 3, lkc = tid & 7;
;     const bf16_t* ga = A + (size_t)lrow * lda + lkc * 8;
;     const bf16_t* gb = B + (size_t)lrow * ldb + lkc * 8;
;     int sbrow[NT];
; #pragma unroll
;     for (int i = 0; i < NT; ++i) { const int g = lrow + 32 * i, W_ = 16 * NT, rem = g % W_; sbrow[i] = (g / W_) * W_ + (rem % NT) * 16 + rem / NT; }
;     u32x4 ra0[4], rb0[NT];
; #pragma unroll
;     for (int i = 0; i < 4; ++i) ra0[i] = *(const u32x4*)(ga + (size_t)(32 * i) * lda);
; #pragma unroll
;     for (int i = 0; i < NT; ++i) rb0[i] = *(const u32x4*)(gb + (size_t)(32 * i) * ldb);
;     const int nk = K >> 6;
; __device__ __forceinline__ void phase_gemm_resid(const bf16_t* A, int lda, int K, const bf16_t* W, const float* X, float* Y, float scale, bf16_t* sm) {
;     const int G = gridDim.x, NTILES = 136 * 8;
;     const int nfull = (NTILES / G) * G;
;     for (int t = blockIdx.x; t < nfull; t += G) resid_tile<4>(t >> 3, (t & 7) * 128, A, lda, K, W, X, Y, scale, sm);
;     for (int u = blockIdx.x; u < 2 * (NTILES - nfull); u += G) {
;         const int t = nfull + (u >> 1);
;         resid_tile<2>(t >> 3, (t & 7) * 128 + (u & 1) * 64, A, lda, K, W, X, Y, scale, sm);
.LBB0_40:
	s_ashr_i32 s2, s78, 1
	s_add_i32 s2, s2, s1
	v_mov_b32_e32 v72, v192
	v_mov_b32_e32 v28, v192
	s_ashr_i32 s52, s2, 3
	s_lshl_b32 s2, s2, 7
	v_ashrrev_i32_e32 v0, 31, v28
	s_lshl_b32 s49, s78, 6
	s_ashr_i32 s53, s52, 31
	v_ashrrev_i32_e32 v26, 3, v28
	v_lshrrev_b32_e32 v0, 27, v0
	s_and_b32 s2, s2, 0x380
	s_and_b32 s49, s49, 64
	s_lshl_b64 s[54:55], s[52:53], s39
	v_add_u32_e32 v0, v26, v0
	s_or_b32 s2, s2, s49
	s_lshl_b64 s[54:55], s[54:55], 1
	v_lshrrev_b32_e32 v1, 5, v0
	s_add_u32 s76, s12, s54
	v_mul_i32_i24_e32 v1, 32, v1
	s_addc_u32 s77, s11, s55
	s_lshl_b32 s49, s2, s74
	v_sub_u32_e32 v29, v26, v1
	s_lshl_b32 s53, s49, 1
	v_and_b32_e32 v30, 0x7ffffe0, v0
	v_lshrrev_b16_e32 v0, 7, v29
	v_ashrrev_i32_e32 v27, 31, v26
	s_add_u32 s82, s13, s53
	v_and_b32_e32 v31, 1, v0
	v_lshlrev_b64 v[0:1], s74, v[26:27]
	s_addc_u32 s83, s94, 0
	v_lshlrev_b64 v[58:59], 1, v[0:1]
	v_lshlrev_b32_e32 v2, 4, v28
	v_lshl_add_u64 v[0:1], s[82:83], 0, v[58:59]
	v_and_b32_e32 v12, 0x70, v2
	v_lshl_add_u64 v[8:9], s[76:77], 0, v[58:59]
	v_lshl_add_u64 v[4:5], v[0:1], 0, v[12:13]
	v_lshl_add_u64 v[14:15], v[8:9], 0, v[12:13]
	s_mov_b32 s49, s87
	s_mov_b32 s51, s87
	v_lshl_add_u64 v[0:1], v[4:5], 0, s[86:87]
	v_lshl_add_u64 v[8:9], v[14:15], 0, s[86:87]
	v_lshl_add_u64 v[16:17], v[14:15], 0, s[48:49]
	v_lshl_add_u64 v[22:23], v[14:15], 0, s[50:51]
	s_nop 0
	v_mov_b32_e32 v250, v4
	v_mov_b32_e32 v251, v5
	s_nop 0
	v_mov_b32_e32 v248, v14
	v_mov_b32_e32 v249, v15
	s_nop 0
	s_nop 0
	s_nop 0
	v_add_u16_e32 v27, v29, v31
	v_ashrrev_i16_sdwa v31, v195, sext(v27) dst_sel:DWORD dst_unused:UNUSED_PAD src0_sel:DWORD src1_sel:BYTE_0
	v_and_b32_e32 v27, 0xfe, v27
	v_sub_u16_e32 v27, v29, v27
	v_lshlrev_b32_sdwa v27, v198, sext(v27) dst_sel:DWORD dst_unused:UNUSED_PAD src0_sel:DWORD src1_sel:BYTE_0
	v_bfe_i32 v29, v31, 0, 16
	v_add3_u32 v27, v30, v29, v27
	v_add_u32_e32 v29, 32, v26
	v_ashrrev_i32_e32 v30, 31, v29
	v_lshrrev_b32_e32 v30, 27, v30
	v_add_u32_e32 v30, v29, v30
	v_and_b32_e32 v30, 0xffffffe0, v30
	v_sub_u32_e32 v29, v29, v30
	v_lshrrev_b16_e32 v31, 7, v29
	v_and_b32_e32 v31, 1, v31
	v_add_u16_e32 v31, v29, v31
	v_ashrrev_i16_sdwa v32, v195, sext(v31) dst_sel:DWORD dst_unused:UNUSED_PAD src0_sel:DWORD src1_sel:BYTE_0
	v_and_b32_e32 v31, 0xfe, v31
	v_sub_u16_e32 v29, v29, v31
	v_lshlrev_b32_sdwa v29, v198, sext(v29) dst_sel:DWORD dst_unused:UNUSED_PAD src0_sel:DWORD src1_sel:BYTE_0
	v_bfe_i32 v31, v32, 0, 16
	v_add3_u32 v29, v30, v31, v29
	v_and_b32_e32 v30, 48, v28
	v_and_b32_e32 v31, 15, v28
	v_lshrrev_b32_e32 v28, 1, v28
	v_and_or_b32 v32, v28, s3, v31
	v_and_or_b32 v28, v28, 32, v31
	v_mul_lo_u32 v31, v32, s89
	v_mul_lo_u32 v32, v26, s89
	v_mul_lo_u32 v33, v27, s89
	v_lshl_add_u64 v[26:27], v[12:13], 0, s[54:55]
	v_lshl_add_u64 v[60:61], s[24:25], 0, v[26:27]
	v_lshl_add_u64 v[62:63], s[40:41], 0, v[26:27]
	v_lshl_add_u64 v[64:65], s[42:43], 0, v[26:27]
	v_lshl_add_u64 v[66:67], s[18:19], 0, v[26:27]
	v_or_b32_e32 v26, s53, v12
	v_mov_b32_e32 v27, v13
	v_mul_u32_u24_e32 v28, 0xa0, v28
	v_mul_lo_u32 v29, v29, s89
	v_lshl_add_u64 v[68:69], s[44:45], 0, v[26:27]
	v_lshl_add_u64 v[70:71], s[46:47], 0, v[26:27]
	v_mov_b32_e32 v26, 0
	v_add_u32_e32 v74, v12, v32
	v_add_u32_e32 v75, v12, v33
	v_add_u32_e32 v76, v12, v29
	v_add_u32_e32 v73, v30, v31
	v_add_u32_e32 v12, v30, v28
	s_mov_b32 s49, s75
	v_mov_b32_e32 v27, v26
	v_mov_b32_e32 v28, v26
	v_mov_b32_e32 v29, v26
	v_mov_b32_e32 v54, v26
	v_mov_b32_e32 v55, v26
	v_mov_b32_e32 v56, v26
	v_mov_b32_e32 v57, v26
	v_mov_b32_e32 v50, v26
	v_mov_b32_e32 v51, v26
	v_mov_b32_e32 v52, v26
	v_mov_b32_e32 v53, v26
	v_mov_b32_e32 v46, v26
	v_mov_b32_e32 v47, v26
	v_mov_b32_e32 v48, v26
	v_mov_b32_e32 v49, v26
	v_mov_b32_e32 v42, v26
	v_mov_b32_e32 v43, v26
	v_mov_b32_e32 v44, v26
	v_mov_b32_e32 v45, v26
	v_mov_b32_e32 v38, v26
	v_mov_b32_e32 v39, v26
	v_mov_b32_e32 v40, v26
	v_mov_b32_e32 v41, v26
	v_mov_b32_e32 v34, v26
	v_mov_b32_e32 v35, v26
	v_mov_b32_e32 v36, v26
	v_mov_b32_e32 v37, v26
	v_mov_b32_e32 v30, v26
	v_mov_b32_e32 v31, v26
	v_mov_b32_e32 v32, v26
	v_mov_b32_e32 v33, v26
	v_writelane_b32 v234, s90, 0
	v_writelane_b32 v234, s91, 1
	v_writelane_b32 v234, s92, 2
	v_writelane_b32 v234, s93, 3
	v_writelane_b32 v234, s94, 4
	v_writelane_b32 v234, s95, 5
	v_bfe_u32 v160, v192, 3, 3
	v_and_b32_e32 v161, 7, v192
	v_xor_b32_e32 v161, v160, v161
	v_lshlrev_b32_e32 v161, 4, v161
	v_lshrrev_b32_e32 v162, 6, v192
	v_lshl_add_u32 v163, v162, 5, v160
	s_lshl_b32 s95, s96, 1
	v_mul_u32_u24_e32 v163, s95, v163
	v_add_u32_e32 v236, v163, v161
	s_lshl_b32 s95, s96, 4
	s_sub_u32 s95, s95, 0x400
	v_add_u32_e32 v237, s95, v236
	v_add_u32_e32 v238, s95, v237
	v_add_u32_e32 v239, s95, v238
	v_lshrrev_b32_e32 v163, 7, v192
	v_bfe_u32 v162, v192, 6, 1
	v_lshlrev_b32_e32 v163, 5, v163
	v_lshl_add_u32 v163, v160, 1, v163
	v_add_u32_e32 v163, v162, v163
	s_lshl_b32 s95, s96, 1
	v_mul_u32_u24_e32 v163, s95, v163
	v_add_u32_e32 v240, v163, v161
	s_mul_i32 s95, s96, 32
	s_sub_u32 s95, s95, 0x400
	v_add_u32_e32 v241, s95, v240
	v_and_b32_e32 v160, 15, v192
	v_bfe_u32 v161, v192, 4, 2
	v_and_b32_e32 v162, 7, v160
	v_xor_b32_e32 v161, v161, v162
	v_lshlrev_b32_e32 v161, 4, v161
	v_lshl_add_u32 v161, v160, 7, v161
	v_lshrrev_b32_e32 v162, 7, v192
	v_lshl_add_u32 v244, v162, 13, v161
	v_bfe_u32 v162, v192, 6, 1
	v_lshl_add_u32 v246, v162, 12, v161
	v_add_u32_e32 v246, 0x4000, v246
	v_xor_b32_e32 v245, 64, v244
	v_xor_b32_e32 v247, 64, v246
	v_lshrrev_b32_e32 v160, 6, v192
	s_nop 0
	v_readfirstlane_b32 s94, v160
	v_readfirstlane_b32 s90, v248
	v_readfirstlane_b32 s91, v249
	v_readfirstlane_b32 s92, v250
	v_readfirstlane_b32 s93, v251
	s_lshl_b32 s95, s96, 4
	s_mul_i32 s95, s94, s95
	s_sub_u32 s90, s90, s95
	s_subb_u32 s91, s91, 0
	s_lshl_b32 s95, s96, 4
	s_mul_i32 s95, s94, s95
	s_sub_u32 s92, s92, s95
	s_subb_u32 s93, s93, 0
	s_lshl_b32 s94, s94, 10
	s_waitcnt lgkmcnt(0)
	s_barrier
; template <int NT>
; __device__ __forceinline__ void gemm_tile(f32x4 (&acc)[4][NT], const bf16_t* A, int lda, const bf16_t* B, int ldb, int K, bf16_t* sm) {
;     ...
;     for (int kt = 0; kt < nk; ++kt) {
;         lds_barrier();
; #pragma unroll
;         for (int i = 0; i < 4; ++i) *(u32x4*)(sA + (lrow + 32 * i) * LDT + lkc * 8) = ra0[i];
; #pragma unroll
;         for (int i = 0; i < NT; ++i) *(u32x4*)(sB + sbrow[i] * LDT + lkc * 8) = rb0[i];
;         lds_barrier();
;         if (kt + 1 < nk) {
;             ga += 64; gb += 64;
; #pragma unroll
;             for (int i = 0; i < 4; ++i) ra0[i] = *(const u32x4*)(ga + (size_t)(32 * i) * lda);
; #pragma unroll
;             for (int i = 0; i < NT; ++i) rb0[i] = *(const u32x4*)(gb + (size_t)(32 * i) * ldb);
;         }
;         __builtin_amdgcn_sched_barrier(0);
;         gemm_compute<NT>(acc, sA, sB, wr, wc, fr, fq);
	s_lshl_b32 s95, s94, 2
	s_add_u32 m0, s95, 0x0
	s_nop 0
	global_load_lds_dwordx4 v236, s[90:91]
	global_load_lds_dwordx4 v237, s[90:91] offset:1024
	global_load_lds_dwordx4 v238, s[90:91] offset:2048
	global_load_lds_dwordx4 v239, s[90:91] offset:3072
	s_mul_i32 s95, s94, 2
	s_add_u32 m0, s95, 0x4000
	s_nop 0
	global_load_lds_dwordx4 v240, s[92:93]
	global_load_lds_dwordx4 v241, s[92:93] offset:1024
	s_add_u32 s90, s90, 0x80
	s_addc_u32 s91, s91, 0
	s_add_u32 s92, s92, 0x80
	s_addc_u32 s93, s93, 0
	s_waitcnt vmcnt(0)
	s_barrier
	s_lshl_b32 s95, s94, 2
	s_add_u32 m0, s95, 0x8000
	s_nop 0
	global_load_lds_dwordx4 v236, s[90:91]
	global_load_lds_dwordx4 v237, s[90:91] offset:1024
	global_load_lds_dwordx4 v238, s[90:91] offset:2048
	global_load_lds_dwordx4 v239, s[90:91] offset:3072
	s_mul_i32 s95, s94, 2
	s_add_u32 m0, s95, 0xc000
	s_nop 0
	global_load_lds_dwordx4 v240, s[92:93]
	global_load_lds_dwordx4 v241, s[92:93] offset:1024
	s_add_u32 s90, s90, 0x80
	s_addc_u32 s91, s91, 0
	s_add_u32 s92, s92, 0x80
	s_addc_u32 s93, s93, 0
	ds_read_b128 v[78:81], v244 offset:0
	ds_read_b128 v[82:85], v244 offset:2048
	ds_read_b128 v[86:89], v244 offset:4096
	ds_read_b128 v[90:93], v244 offset:6144
	ds_read_b128 v[94:97], v246 offset:0
	ds_read_b128 v[100:103], v246 offset:2048
	s_lshr_b32 s95, s96, 7
	s_add_i32 s95, s95, -2
	s_cmp_eq_u32 s95, 0
	s_cbranch_scc1 .Lgemm_x41
.Lgemm_k41:
	v_writelane_b32 v234, s95, 6
	ds_read_b128 v[160:163], v245 offset:0
	ds_read_b128 v[164:167], v245 offset:2048
	ds_read_b128 v[168:171], v245 offset:4096
	ds_read_b128 v[172:175], v245 offset:6144
	ds_read_b128 v[176:179], v247 offset:0
	ds_read_b128 v[180:183], v247 offset:2048
	s_setprio 1
	s_waitcnt lgkmcnt(7)
	v_mfma_f32_16x16x32_bf16 v[26:29], v[94:97], v[78:81], v[26:29]
	s_waitcnt lgkmcnt(6)
	v_mfma_f32_16x16x32_bf16 v[54:57], v[100:103], v[78:81], v[54:57]
	v_mfma_f32_16x16x32_bf16 v[50:53], v[94:97], v[82:85], v[50:53]
	v_mfma_f32_16x16x32_bf16 v[46:49], v[100:103], v[82:85], v[46:49]
	v_mfma_f32_16x16x32_bf16 v[42:45], v[94:97], v[86:89], v[42:45]
	v_mfma_f32_16x16x32_bf16 v[38:41], v[100:103], v[86:89], v[38:41]
	v_mfma_f32_16x16x32_bf16 v[34:37], v[94:97], v[90:93], v[34:37]
	v_mfma_f32_16x16x32_bf16 v[30:33], v[100:103], v[90:93], v[30:33]
	s_setprio 0
	s_waitcnt vmcnt(0) lgkmcnt(0)
	s_barrier
	ds_read_b128 v[78:81], v244 offset:32768
	ds_read_b128 v[82:85], v244 offset:34816
	ds_read_b128 v[86:89], v244 offset:36864
	ds_read_b128 v[90:93], v244 offset:38912
	ds_read_b128 v[94:97], v246 offset:32768
	ds_read_b128 v[100:103], v246 offset:34816
	s_setprio 1
	v_mfma_f32_16x16x32_bf16 v[26:29], v[176:179], v[160:163], v[26:29]
	s_lshl_b32 s95, s94, 2
	s_add_u32 m0, s95, 0x0
	s_nop 0
	global_load_lds_dwordx4 v236, s[90:91]
	v_mfma_f32_16x16x32_bf16 v[54:57], v[180:183], v[160:163], v[54:57]
	v_mfma_f32_16x16x32_bf16 v[50:53], v[176:179], v[164:167], v[50:53]
	global_load_lds_dwordx4 v237, s[90:91] offset:1024
	v_mfma_f32_16x16x32_bf16 v[46:49], v[180:183], v[164:167], v[46:49]
	v_mfma_f32_16x16x32_bf16 v[42:45], v[176:179], v[168:171], v[42:45]
	global_load_lds_dwordx4 v238, s[90:91] offset:2048
	v_mfma_f32_16x16x32_bf16 v[38:41], v[180:183], v[168:171], v[38:41]
	v_mfma_f32_16x16x32_bf16 v[34:37], v[176:179], v[172:175], v[34:37]
	global_load_lds_dwordx4 v239, s[90:91] offset:3072
	v_mfma_f32_16x16x32_bf16 v[30:33], v[180:183], v[172:175], v[30:33]
	s_mul_i32 s95, s94, 2
	s_add_u32 m0, s95, 0x4000
	s_nop 0
	global_load_lds_dwordx4 v240, s[92:93]
	global_load_lds_dwordx4 v241, s[92:93] offset:1024
	s_add_u32 s90, s90, 0x80
	s_addc_u32 s91, s91, 0
	s_add_u32 s92, s92, 0x80
	s_addc_u32 s93, s93, 0
	s_setprio 0
	ds_read_b128 v[160:163], v245 offset:32768
	ds_read_b128 v[164:167], v245 offset:34816
	ds_read_b128 v[168:171], v245 offset:36864
	ds_read_b128 v[172:175], v245 offset:38912
	ds_read_b128 v[176:179], v247 offset:32768
	ds_read_b128 v[180:183], v247 offset:34816
	s_setprio 1
	s_waitcnt lgkmcnt(7)
	v_mfma_f32_16x16x32_bf16 v[26:29], v[94:97], v[78:81], v[26:29]
	s_waitcnt lgkmcnt(6)
	v_mfma_f32_16x16x32_bf16 v[54:57], v[100:103], v[78:81], v[54:57]
	v_mfma_f32_16x16x32_bf16 v[50:53], v[94:97], v[82:85], v[50:53]
	v_mfma_f32_16x16x32_bf16 v[46:49], v[100:103], v[82:85], v[46:49]
	v_mfma_f32_16x16x32_bf16 v[42:45], v[94:97], v[86:89], v[42:45]
	v_mfma_f32_16x16x32_bf16 v[38:41], v[100:103], v[86:89], v[38:41]
	v_mfma_f32_16x16x32_bf16 v[34:37], v[94:97], v[90:93], v[34:37]
	v_mfma_f32_16x16x32_bf16 v[30:33], v[100:103], v[90:93], v[30:33]
	s_setprio 0
	s_waitcnt vmcnt(0) lgkmcnt(0)
	s_barrier
	ds_read_b128 v[78:81], v244 offset:0
	ds_read_b128 v[82:85], v244 offset:2048
	ds_read_b128 v[86:89], v244 offset:4096
	ds_read_b128 v[90:93], v244 offset:6144
	ds_read_b128 v[94:97], v246 offset:0
	ds_read_b128 v[100:103], v246 offset:2048
	s_setprio 1
	v_mfma_f32_16x16x32_bf16 v[26:29], v[176:179], v[160:163], v[26:29]
	s_lshl_b32 s95, s94, 2
	s_add_u32 m0, s95, 0x8000
	s_nop 0
	global_load_lds_dwordx4 v236, s[90:91]
	v_mfma_f32_16x16x32_bf16 v[54:57], v[180:183], v[160:163], v[54:57]
	v_mfma_f32_16x16x32_bf16 v[50:53], v[176:179], v[164:167], v[50:53]
	global_load_lds_dwordx4 v237, s[90:91] offset:1024
	v_mfma_f32_16x16x32_bf16 v[46:49], v[180:183], v[164:167], v[46:49]
	v_mfma_f32_16x16x32_bf16 v[42:45], v[176:179], v[168:171], v[42:45]
	global_load_lds_dwordx4 v238, s[90:91] offset:2048
	v_mfma_f32_16x16x32_bf16 v[38:41], v[180:183], v[168:171], v[38:41]
	v_mfma_f32_16x16x32_bf16 v[34:37], v[176:179], v[172:175], v[34:37]
	global_load_lds_dwordx4 v239, s[90:91] offset:3072
	v_mfma_f32_16x16x32_bf16 v[30:33], v[180:183], v[172:175], v[30:33]
	s_mul_i32 s95, s94, 2
	s_add_u32 m0, s95, 0xc000
	s_nop 0
	global_load_lds_dwordx4 v240, s[92:93]
	global_load_lds_dwordx4 v241, s[92:93] offset:1024
	s_add_u32 s90, s90, 0x80
	s_addc_u32 s91, s91, 0
	s_add_u32 s92, s92, 0x80
	s_addc_u32 s93, s93, 0
	s_setprio 0
	v_readlane_b32 s95, v234, 6
	s_add_i32 s95, s95, -1
	s_cmp_lg_u32 s95, 0
	s_cbranch_scc1 .Lgemm_k41
; template <int NT>
; __device__ __forceinline__ void gemm_tile(f32x4 (&acc)[4][NT], const bf16_t* A, int lda, const bf16_t* B, int ldb, int K, bf16_t* sm) {
;     ...
;     for (int kt = 0; kt < nk; ++kt) {
;         lds_barrier();
; #pragma unroll
;         for (int i = 0; i < 4; ++i) *(u32x4*)(sA + (lrow + 32 * i) * LDT + lkc * 8) = ra0[i];
; #pragma unroll
;         for (int i = 0; i < NT; ++i) *(u32x4*)(sB + sbrow[i] * LDT + lkc * 8) = rb0[i];
;         lds_barrier();
;         if (kt + 1 < nk) {
;             ga += 64; gb += 64;
; #pragma unroll
;             for (int i = 0; i < 4; ++i) ra0[i] = *(const u32x4*)(ga + (size_t)(32 * i) * lda);
; #pragma unroll
;             for (int i = 0; i < NT; ++i) rb0[i] = *(const u32x4*)(gb + (size_t)(32 * i) * ldb);
;         }
;         __builtin_amdgcn_sched_barrier(0);
;         gemm_compute<NT>(acc, sA, sB, wr, wc, fr, fq);
;         __builtin_amdgcn_sched_barrier(0);
;     }
.Lgemm_x41:
	ds_read_b128 v[160:163], v245 offset:0
	ds_read_b128 v[164:167], v245 offset:2048
	ds_read_b128 v[168:171], v245 offset:4096
	ds_read_b128 v[172:175], v245 offset:6144
	ds_read_b128 v[176:179], v247 offset:0
	ds_read_b128 v[180:183], v247 offset:2048
	s_setprio 1
	s_waitcnt lgkmcnt(7)
	v_mfma_f32_16x16x32_bf16 v[26:29], v[94:97], v[78:81], v[26:29]
	s_waitcnt lgkmcnt(6)
	v_mfma_f32_16x16x32_bf16 v[54:57], v[100:103], v[78:81], v[54:57]
	v_mfma_f32_16x16x32_bf16 v[50:53], v[94:97], v[82:85], v[50:53]
	v_mfma_f32_16x16x32_bf16 v[46:49], v[100:103], v[82:85], v[46:49]
	v_mfma_f32_16x16x32_bf16 v[42:45], v[94:97], v[86:89], v[42:45]
	v_mfma_f32_16x16x32_bf16 v[38:41], v[100:103], v[86:89], v[38:41]
	v_mfma_f32_16x16x32_bf16 v[34:37], v[94:97], v[90:93], v[34:37]
	v_mfma_f32_16x16x32_bf16 v[30:33], v[100:103], v[90:93], v[30:33]
	s_setprio 0
	s_waitcnt vmcnt(0) lgkmcnt(0)
	s_barrier
	ds_read_b128 v[78:81], v244 offset:32768
	ds_read_b128 v[82:85], v244 offset:34816
	ds_read_b128 v[86:89], v244 offset:36864
	ds_read_b128 v[90:93], v244 offset:38912
	ds_read_b128 v[94:97], v246 offset:32768
	ds_read_b128 v[100:103], v246 offset:34816
	s_setprio 1
	v_mfma_f32_16x16x32_bf16 v[26:29], v[176:179], v[160:163], v[26:29]
	s_lshl_b32 s95, s94, 2
	s_add_u32 m0, s95, 0x0
	s_nop 0
	global_load_lds_dwordx4 v236, s[90:91]
	v_mfma_f32_16x16x32_bf16 v[54:57], v[180:183], v[160:163], v[54:57]
	v_mfma_f32_16x16x32_bf16 v[50:53], v[176:179], v[164:167], v[50:53]
	global_load_lds_dwordx4 v237, s[90:91] offset:1024
	v_mfma_f32_16x16x32_bf16 v[46:49], v[180:183], v[164:167], v[46:49]
	v_mfma_f32_16x16x32_bf16 v[42:45], v[176:179], v[168:171], v[42:45]
	global_load_lds_dwordx4 v238, s[90:91] offset:2048
	v_mfma_f32_16x16x32_bf16 v[38:41], v[180:183], v[168:171], v[38:41]
	v_mfma_f32_16x16x32_bf16 v[34:37], v[176:179], v[172:175], v[34:37]
	global_load_lds_dwordx4 v239, s[90:91] offset:3072
	v_mfma_f32_16x16x32_bf16 v[30:33], v[180:183], v[172:175], v[30:33]
	s_mul_i32 s95, s94, 2
	s_add_u32 m0, s95, 0x4000
	s_nop 0
	global_load_lds_dwordx4 v240, s[92:93]
	global_load_lds_dwordx4 v241, s[92:93] offset:1024
	s_add_u32 s90, s90, 0x80
	s_addc_u32 s91, s91, 0
	s_add_u32 s92, s92, 0x80
	s_addc_u32 s93, s93, 0
	s_setprio 0
	ds_read_b128 v[160:163], v245 offset:32768
	ds_read_b128 v[164:167], v245 offset:34816
	ds_read_b128 v[168:171], v245 offset:36864
	ds_read_b128 v[172:175], v245 offset:38912
	ds_read_b128 v[176:179], v247 offset:32768
	ds_read_b128 v[180:183], v247 offset:34816
	s_setprio 1
	s_waitcnt lgkmcnt(7)
	v_mfma_f32_16x16x32_bf16 v[26:29], v[94:97], v[78:81], v[26:29]
	s_waitcnt lgkmcnt(6)
	v_mfma_f32_16x16x32_bf16 v[54:57], v[100:103], v[78:81], v[54:57]
	v_mfma_f32_16x16x32_bf16 v[50:53], v[94:97], v[82:85], v[50:53]
	v_mfma_f32_16x16x32_bf16 v[46:49], v[100:103], v[82:85], v[46:49]
	v_mfma_f32_16x16x32_bf16 v[42:45], v[94:97], v[86:89], v[42:45]
	v_mfma_f32_16x16x32_bf16 v[38:41], v[100:103], v[86:89], v[38:41]
	v_mfma_f32_16x16x32_bf16 v[34:37], v[94:97], v[90:93], v[34:37]
	v_mfma_f32_16x16x32_bf16 v[30:33], v[100:103], v[90:93], v[30:33]
	s_setprio 0
	s_waitcnt vmcnt(0) lgkmcnt(0)
	s_barrier
	ds_read_b128 v[78:81], v244 offset:0
	ds_read_b128 v[82:85], v244 offset:2048
	ds_read_b128 v[86:89], v244 offset:4096
	ds_read_b128 v[90:93], v244 offset:6144
	ds_read_b128 v[94:97], v246 offset:0
	ds_read_b128 v[100:103], v246 offset:2048
	s_setprio 1
	v_mfma_f32_16x16x32_bf16 v[26:29], v[176:179], v[160:163], v[26:29]
	s_lshl_b32 s92, s96, 1
	s_sub_u32 s92, s92, 0x100
	s_mov_b32 s93, 0
	v_lshl_add_u64 v[60:61], v[60:61], 0, s[92:93]
	v_lshl_add_u64 v[62:63], v[62:63], 0, s[92:93]
	v_lshl_add_u64 v[64:65], v[64:65], 0, s[92:93]
	v_lshl_add_u64 v[66:67], v[66:67], 0, s[92:93]
	v_lshl_add_u64 v[68:69], v[68:69], 0, s[92:93]
	v_lshl_add_u64 v[70:71], v[70:71], 0, s[92:93]
	v_readlane_b32 s90, v234, 0
	v_readlane_b32 s91, v234, 1
	v_readlane_b32 s92, v234, 2
	v_readlane_b32 s93, v234, 3
	v_readlane_b32 s94, v234, 4
	v_readlane_b32 s95, v234, 5
	s_mov_b32 s49, 0
	s_nop 3
	v_mfma_f32_16x16x32_bf16 v[54:57], v[180:183], v[160:163], v[54:57]
	v_mfma_f32_16x16x32_bf16 v[50:53], v[176:179], v[164:167], v[50:53]
	v_lshl_add_u64 v[0:1], v[66:67], 0, v[58:59]
	v_mfma_f32_16x16x32_bf16 v[46:49], v[180:183], v[164:167], v[46:49]
	v_mfma_f32_16x16x32_bf16 v[42:45], v[176:179], v[168:171], v[42:45]
	global_load_dwordx4 v[18:21], v[0:1], off
	v_mfma_f32_16x16x32_bf16 v[38:41], v[180:183], v[168:171], v[38:41]
	v_mfma_f32_16x16x32_bf16 v[34:37], v[176:179], v[172:175], v[34:37]
	v_lshl_add_u64 v[0:1], v[64:65], 0, v[58:59]
	v_mfma_f32_16x16x32_bf16 v[30:33], v[180:183], v[172:175], v[30:33]
	global_load_dwordx4 v[8:11], v[0:1], off
	v_lshl_add_u64 v[0:1], v[62:63], 0, v[58:59]
	global_load_dwordx4 v[14:17], v[0:1], off
	v_lshl_add_u64 v[0:1], v[60:61], 0, v[58:59]
	global_load_dwordx4 v[22:25], v[0:1], off
	v_lshl_add_u64 v[0:1], v[70:71], 0, v[58:59]
	global_load_dwordx4 v[4:7], v[0:1], off
	v_lshl_add_u64 v[0:1], v[68:69], 0, v[58:59]
	global_load_dwordx4 v[0:3], v[0:1], off
	s_setprio 0
	ds_read_b128 v[160:163], v245 offset:0
	ds_read_b128 v[164:167], v245 offset:2048
	ds_read_b128 v[168:171], v245 offset:4096
	ds_read_b128 v[172:175], v245 offset:6144
	ds_read_b128 v[176:179], v247 offset:0
	ds_read_b128 v[180:183], v247 offset:2048
	s_setprio 1
	s_waitcnt lgkmcnt(7)
	v_mfma_f32_16x16x32_bf16 v[26:29], v[94:97], v[78:81], v[26:29]
	s_waitcnt lgkmcnt(6)
	v_mfma_f32_16x16x32_bf16 v[54:57], v[100:103], v[78:81], v[54:57]
	v_mfma_f32_16x16x32_bf16 v[50:53], v[94:97], v[82:85], v[50:53]
	v_mfma_f32_16x16x32_bf16 v[46:49], v[100:103], v[82:85], v[46:49]
	v_mfma_f32_16x16x32_bf16 v[42:45], v[94:97], v[86:89], v[42:45]
	v_mfma_f32_16x16x32_bf16 v[38:41], v[100:103], v[86:89], v[38:41]
	v_mfma_f32_16x16x32_bf16 v[34:37], v[94:97], v[90:93], v[34:37]
	v_mfma_f32_16x16x32_bf16 v[30:33], v[100:103], v[90:93], v[30:33]
	s_setprio 0
	s_waitcnt lgkmcnt(0)
	s_setprio 1
	v_mfma_f32_16x16x32_bf16 v[26:29], v[176:179], v[160:163], v[26:29]
	v_mfma_f32_16x16x32_bf16 v[54:57], v[180:183], v[160:163], v[54:57]
	v_mfma_f32_16x16x32_bf16 v[50:53], v[176:179], v[164:167], v[50:53]
	v_mfma_f32_16x16x32_bf16 v[46:49], v[180:183], v[164:167], v[46:49]
	v_mfma_f32_16x16x32_bf16 v[42:45], v[176:179], v[168:171], v[42:45]
	v_mfma_f32_16x16x32_bf16 v[38:41], v[180:183], v[168:171], v[38:41]
	v_mfma_f32_16x16x32_bf16 v[34:37], v[176:179], v[172:175], v[34:37]
	v_mfma_f32_16x16x32_bf16 v[30:33], v[180:183], v[172:175], v[30:33]
	s_setprio 0
	s_waitcnt lgkmcnt(0)
	s_barrier
; template <int NT>
; __device__ __forceinline__ void gemm_tile(f32x4 (&acc)[4][NT], const bf16_t* A, int lda, const bf16_t* B, int ldb, int K, bf16_t* sm) {
;     ...
;         for (int i = 0; i < 4; ++i) *(u32x4*)(sA + (lrow + 32 * i) * LDT + lkc * 8) = ra0[i];
; #pragma unroll
;         for (int i = 0; i < NT; ++i) *(u32x4*)(sB + sbrow[i] * LDT + lkc * 8) = rb0[i];
;         lds_barrier();
;         if (kt + 1 < nk) {
;             ga += 64; gb += 64;
; #pragma unroll
;             for (int i = 0; i < 4; ++i) ra0[i] = *(const u32x4*)(ga + (size_t)(32 * i) * lda);
; #pragma unroll
;             for (int i = 0; i < NT; ++i) rb0[i] = *(const u32x4*)(gb + (size_t)(32 * i) * ldb);
;         }
;         __builtin_amdgcn_sched_barrier(0);
;         gemm_compute<NT>(acc, sA, sB, wr, wc, fr, fq);
; template <int NT>
; __device__ __forceinline__ void resid_tile(int tm, int col0, const bf16_t* A, int lda, int K, const bf16_t* W, const float* X, float* Y, float scale, bf16_t* sm) {
;     ...
; #pragma unroll
;     for (int mt = 0; mt < 4; ++mt) {
;         const int row = tm * 128 + wr * 64 + mt * 16 + fr;
;         const int cbase = col0 + wc * 16 * NT + fq * 4 * NT;
;         const size_t o = (size_t)row * 1024 + cbase;
;         float v[4 * NT]; gather_cols<NT>(acc, mt, v);
;         float4 xv[NT];
; #pragma unroll
;         for (int q = 0; q < NT; ++q) xv[q] = *(const float4*)(X + o + 4 * q);
; #pragma unroll
;         for (int q = 0; q < NT; ++q)
;             *(float4*)(Y + o + 4 * q) = make_float4(ALPHA * xv[q].x + scale * v[4 * q], ALPHA * xv[q].y + scale * v[4 * q + 1],
;                                                     ALPHA * xv[q].z + scale * v[4 * q + 2], ALPHA * xv[q].w + scale * v[4 * q + 3]);
	s_waitcnt vmcnt(5)
	ds_write_b128 v74, v[18:21]
	s_waitcnt vmcnt(4)
	ds_write_b128 v74, v[8:11] offset:5120
	s_waitcnt vmcnt(3)
	ds_write_b128 v74, v[14:17] offset:10240
	s_waitcnt vmcnt(2)
	ds_write_b128 v74, v[22:25] offset:15360
	s_waitcnt vmcnt(1)
	ds_write_b128 v75, v[4:7] offset:20480
	s_waitcnt vmcnt(0)
	ds_write_b128 v76, v[0:3] offset:20480
	s_waitcnt lgkmcnt(0)
	s_barrier
	ds_read_b128 v[0:3], v73
	ds_read_b128 v[4:7], v73 offset:2560
	ds_read_b128 v[8:11], v73 offset:5120
	ds_read_b128 v[14:17], v73 offset:7680
	ds_read_b128 v[18:21], v12 offset:20480
	ds_read_b128 v[22:25], v12 offset:23040
	s_setprio 1
	s_waitcnt lgkmcnt(1)
	v_mfma_f32_16x16x32_bf16 v[26:29], v[18:21], v[0:3], v[26:29]
	s_waitcnt lgkmcnt(0)
	v_mfma_f32_16x16x32_bf16 v[0:3], v[22:25], v[0:3], v[54:57]
	v_mfma_f32_16x16x32_bf16 v[50:53], v[18:21], v[4:7], v[50:53]
	v_mfma_f32_16x16x32_bf16 v[4:7], v[22:25], v[4:7], v[46:49]
	v_mfma_f32_16x16x32_bf16 v[42:45], v[18:21], v[8:11], v[42:45]
	v_mfma_f32_16x16x32_bf16 v[38:41], v[22:25], v[8:11], v[38:41]
	v_mfma_f32_16x16x32_bf16 v[18:21], v[18:21], v[14:17], v[34:37]
	v_mfma_f32_16x16x32_bf16 v[22:25], v[22:25], v[14:17], v[30:33]
	s_setprio 0
	ds_read_b128 v[8:11], v73 offset:64
	ds_read_b128 v[14:17], v73 offset:2624
	ds_read_b128 v[30:33], v73 offset:5184
	ds_read_b128 v[34:37], v73 offset:7744
	ds_read_b128 v[46:49], v12 offset:20544
	ds_read_b128 v[54:57], v12 offset:23104
	s_setprio 1
	s_waitcnt lgkmcnt(1)
	v_mfma_f32_16x16x32_bf16 v[26:29], v[46:49], v[8:11], v[26:29]
	s_waitcnt lgkmcnt(0)
	v_mfma_f32_16x16x32_bf16 v[58:61], v[54:57], v[8:11], v[0:3]
	v_mfma_f32_16x16x32_bf16 v[50:53], v[46:49], v[14:17], v[50:53]
	v_mfma_f32_16x16x32_bf16 v[62:65], v[54:57], v[14:17], v[4:7]
	v_mfma_f32_16x16x32_bf16 v[8:11], v[46:49], v[30:33], v[42:45]
	v_mfma_f32_16x16x32_bf16 v[14:17], v[54:57], v[30:33], v[38:41]
	v_mfma_f32_16x16x32_bf16 v[0:3], v[46:49], v[34:37], v[18:21]
	v_mfma_f32_16x16x32_bf16 v[4:7], v[54:57], v[34:37], v[22:25]
	s_setprio 0
	v_ashrrev_i32_e32 v12, 1, v72
	v_and_b32_e32 v12, 0xffffffc0, v12
	v_lshl_add_u32 v12, s52, 7, v12
	v_and_or_b32 v18, v72, 15, v12
	v_lshrrev_b32_e32 v12, 1, v72
	v_and_or_b32 v12, v12, 56, s2
	v_ashrrev_i32_e32 v19, 31, v18
	v_lshlrev_b64 v[20:21], 12, v[18:19]
	v_lshlrev_b32_e32 v12, 2, v12
	v_or_b32_e32 v20, v20, v12
	v_lshl_add_u64 v[24:25], s[56:57], 0, v[20:21]
	v_lshl_add_u64 v[34:35], s[90:91], 0, v[20:21]
	global_load_dwordx4 v[20:23], v[24:25], off offset:16
	global_load_dwordx4 v[30:33], v[24:25], off
	s_add_i32 s78, s78, s62
	s_cmp_ge_i32 s78, s79
	s_waitcnt vmcnt(1)
	v_pk_mul_f32 v[20:21], v[20:21], s[88:89] op_sel_hi:[1,0]
	s_waitcnt vmcnt(0)
	v_pk_mul_f32 v[24:25], v[30:31], s[88:89] op_sel_hi:[1,0]
	v_mov_b32_e32 v30, v26
	v_mov_b32_e32 v31, v58
	v_pk_fma_f32 v[24:25], v[98:99], v[30:31], v[24:25]
	v_pk_mul_f32 v[30:31], v[32:33], s[88:89] op_sel_hi:[1,0]
	v_mov_b32_e32 v58, v27
	v_pk_fma_f32 v[26:27], v[98:99], v[58:59], v[30:31]
	v_mov_b32_e32 v30, v28
	v_mov_b32_e32 v31, v60
	v_pk_fma_f32 v[20:21], v[98:99], v[30:31], v[20:21]
	v_pk_mul_f32 v[22:23], v[22:23], s[88:89] op_sel_hi:[1,0]
	v_mov_b32_e32 v60, v29
	v_pk_fma_f32 v[22:23], v[98:99], v[60:61], v[22:23]
	global_store_dwordx4 v[34:35], v[24:27], off
	global_store_dwordx4 v[34:35], v[20:23], off offset:16
	v_mov_b32_e32 v30, v50
	v_mov_b32_e32 v31, v62
	v_or_b32_e32 v20, 16, v18
	v_ashrrev_i32_e32 v21, 31, v20
	v_lshlrev_b64 v[20:21], 12, v[20:21]
	v_or_b32_e32 v20, v20, v12
	v_lshl_add_u64 v[24:25], s[56:57], 0, v[20:21]
	v_lshl_add_u64 v[28:29], s[90:91], 0, v[20:21]
	global_load_dwordx4 v[20:23], v[24:25], off offset:16
	s_nop 0
	global_load_dwordx4 v[24:27], v[24:25], off
	v_mov_b32_e32 v62, v51
	s_waitcnt vmcnt(1)
	v_pk_mul_f32 v[20:21], v[20:21], s[88:89] op_sel_hi:[1,0]
	s_waitcnt vmcnt(0)
	v_pk_mul_f32 v[24:25], v[24:25], s[88:89] op_sel_hi:[1,0]
	v_pk_mul_f32 v[26:27], v[26:27], s[88:89] op_sel_hi:[1,0]
	v_pk_fma_f32 v[24:25], v[98:99], v[30:31], v[24:25]
	v_mov_b32_e32 v30, v52
	v_mov_b32_e32 v31, v64
	v_pk_fma_f32 v[26:27], v[98:99], v[62:63], v[26:27]
	v_pk_fma_f32 v[20:21], v[98:99], v[30:31], v[20:21]
	v_pk_mul_f32 v[22:23], v[22:23], s[88:89] op_sel_hi:[1,0]
	v_mov_b32_e32 v64, v53
	v_pk_fma_f32 v[22:23], v[98:99], v[64:65], v[22:23]
	global_store_dwordx4 v[28:29], v[24:27], off
	global_store_dwordx4 v[28:29], v[20:23], off offset:16
	v_mov_b32_e32 v31, v14
	v_mov_b32_e32 v14, v9
	v_or_b32_e32 v20, 32, v18
	v_ashrrev_i32_e32 v21, 31, v20
	v_lshlrev_b64 v[20:21], 12, v[20:21]
	v_or_b32_e32 v20, v20, v12
	v_lshl_add_u64 v[24:25], s[56:57], 0, v[20:21]
	v_lshl_add_u64 v[28:29], s[90:91], 0, v[20:21]
	global_load_dwordx4 v[20:23], v[24:25], off offset:16
	s_nop 0
	global_load_dwordx4 v[24:27], v[24:25], off
	v_mov_b32_e32 v30, v8
	s_waitcnt vmcnt(1)
	v_pk_mul_f32 v[8:9], v[20:21], s[88:89] op_sel_hi:[1,0]
	s_waitcnt vmcnt(0)
	v_pk_mul_f32 v[26:27], v[26:27], s[88:89] op_sel_hi:[1,0]
	v_pk_mul_f32 v[24:25], v[24:25], s[88:89] op_sel_hi:[1,0]
	v_pk_fma_f32 v[26:27], v[98:99], v[14:15], v[26:27]
	v_mov_b32_e32 v14, v10
	v_mov_b32_e32 v15, v16
	v_pk_fma_f32 v[24:25], v[98:99], v[30:31], v[24:25]
	v_pk_fma_f32 v[8:9], v[98:99], v[14:15], v[8:9]
	v_pk_mul_f32 v[14:15], v[22:23], s[88:89] op_sel_hi:[1,0]
	v_mov_b32_e32 v16, v11
	v_pk_fma_f32 v[10:11], v[98:99], v[16:17], v[14:15]
	global_store_dwordx4 v[28:29], v[24:27], off
	global_store_dwordx4 v[28:29], v[8:11], off offset:16
	v_mov_b32_e32 v21, v4
	v_mov_b32_e32 v4, v1
	v_or_b32_e32 v8, 48, v18
	v_ashrrev_i32_e32 v9, 31, v8
	v_lshlrev_b64 v[8:9], 12, v[8:9]
	v_or_b32_e32 v8, v8, v12
	v_lshl_add_u64 v[14:15], s[56:57], 0, v[8:9]
	v_lshl_add_u64 v[18:19], s[90:91], 0, v[8:9]
	global_load_dwordx4 v[8:11], v[14:15], off offset:16
	s_nop 0
	global_load_dwordx4 v[14:17], v[14:15], off
	v_mov_b32_e32 v20, v0
	s_waitcnt vmcnt(1)
	v_pk_mul_f32 v[0:1], v[8:9], s[88:89] op_sel_hi:[1,0]
	s_waitcnt vmcnt(0)
	v_pk_mul_f32 v[16:17], v[16:17], s[88:89] op_sel_hi:[1,0]
	v_pk_mul_f32 v[14:15], v[14:15], s[88:89] op_sel_hi:[1,0]
	v_pk_fma_f32 v[16:17], v[98:99], v[4:5], v[16:17]
	v_mov_b32_e32 v4, v2
	v_mov_b32_e32 v5, v6
	v_pk_fma_f32 v[14:15], v[98:99], v[20:21], v[14:15]
	v_pk_fma_f32 v[0:1], v[98:99], v[4:5], v[0:1]
	v_pk_mul_f32 v[4:5], v[10:11], s[88:89] op_sel_hi:[1,0]
	v_mov_b32_e32 v6, v3
	v_pk_fma_f32 v[2:3], v[98:99], v[6:7], v[4:5]
	global_store_dwordx4 v[18:19], v[14:17], off
	global_store_dwordx4 v[18:19], v[0:3], off offset:16
	s_cbranch_scc0 .LBB0_40
